# selected loop rounds of up to 5 tiles (one more staging pair, fifth LDS slot below the selection masks)
# baseline (speedup 1.0000x reference)
; #define LAS __attribute__((address_space(3)))
; __device__ __forceinline__ void tile_issue(TileRegs& r, const int tid, const bf16_t* ksrc, const bf16_t* vsrc, size_t ld, int p0, int pmax) {
;     const int kkey = tid >> 3, kseg = tid & 7, pk = p0 + kkey; const int vkey = tid & 63, vseg = tid >> 6, pv = p0 + vkey;
;     r.k = (u32x4){0u, 0u, 0u, 0u}; r.v = (u32x4){0u, 0u, 0u, 0u};
;     if (pk >= 0 && pk <= pmax) r.k = *(const u32x4*)(ksrc + (size_t)pk * ld + kseg * 8);
;     if (pv >= 0 && pv <= pmax) r.v = *(const u32x4*)(vsrc + (size_t)pv * ld + vseg * 8); }
; __device__ __forceinline__ void nsa_unit(LAS unsigned char* lds, const Ctx& P, int l, int b, int hkv, int tb) {
;     ...
;         while (Ur != 0ull) {
;             const int ja = __builtin_ctzll(Ur); Ur &= Ur - 1ull; const bool hasb = Ur != 0ull; int jb = 0; if (hasb) { jb = __builtin_ctzll(Ur); Ur &= Ur - 1ull; }
;             __syncthreads();
;             load2(kb, vb, LDH, ja * 64, jb * 64, hasb, SEQ - 1);
;             __syncthreads();
; #pragma unroll
;             for (int sl = 0; sl < 2; ++sl) if (sl == 0 || hasb) {
;                 const int j = sl ? jb : ja; const LAS bf16_t* Ks = KV + sl * 9216; const LAS bf16_t* Vt = Ks + 4608;
.LBB0_407:
	v_add_u32_e32 v102, v150, v148
	v_lshrrev_b32_e32 v78, 2, v97
	v_lshl_add_u32 v78, v103, 2, v78
	v_mul_u32_u24_e32 v78, 0xa0, v78
	v_and_b32_e32 v79, 3, v97
	v_lshl_add_u32 v104, v79, 3, v78
	v_add_u32_e32 v192, 0xc000, v146
	s_mov_b64 s[14:15], s[0:1]
	s_mov_b32 s13, 0
	s_ff1_i32_b64 s0, s[14:15]
	s_add_u32 s4, s14, -1
	s_addc_u32 s5, s15, -1
	s_and_b64 s[14:15], s[14:15], s[4:5]
	s_mov_b32 s13, 1
	s_lshl_b32 s4, s0, 6
	v_add_u32_e32 v54, s4, v144
	v_mul_lo_u32 v54, v54, s75
	v_mov_b32_e32 v55, v1
	v_lshl_add_u64 v[54:55], v[54:55], 1, v[88:89]
	global_load_dwordx4 v[230:233], v[54:55], off
	global_load_dwordx4 v[114:117], v[54:55], off offset:512
	s_cmp_eq_u64 s[14:15], 0
	s_cbranch_scc1 .Lsl3_xd_1
	s_ff1_i32_b64 s1, s[14:15]
	s_add_u32 s4, s14, -1
	s_addc_u32 s5, s15, -1
	s_and_b64 s[14:15], s[14:15], s[4:5]
	s_mov_b32 s13, 2
	s_lshl_b32 s4, s1, 6
	v_add_u32_e32 v54, s4, v144
	v_mul_lo_u32 v54, v54, s75
	v_mov_b32_e32 v55, v1
	v_lshl_add_u64 v[54:55], v[54:55], 1, v[88:89]
	global_load_dwordx4 v[134:137], v[54:55], off
	global_load_dwordx4 v[156:159], v[54:55], off offset:512
	s_cmp_eq_u64 s[14:15], 0
	s_cbranch_scc1 .Lsl3_xd_1
	s_ff1_i32_b64 s31, s[14:15]
	s_add_u32 s4, s14, -1
	s_addc_u32 s5, s15, -1
	s_and_b64 s[14:15], s[14:15], s[4:5]
	s_mov_b32 s13, 3
	s_lshl_b32 s4, s31, 6
	v_add_u32_e32 v54, s4, v144
	v_mul_lo_u32 v54, v54, s75
	v_mov_b32_e32 v55, v1
	v_lshl_add_u64 v[54:55], v[54:55], 1, v[88:89]
	global_load_dwordx4 v[174:177], v[54:55], off
	global_load_dwordx4 v[178:181], v[54:55], off offset:512
	s_cmp_eq_u64 s[14:15], 0
	s_cbranch_scc1 .Lsl3_xd_1
	s_ff1_i32_b64 s32, s[14:15]
	s_add_u32 s4, s14, -1
	s_addc_u32 s5, s15, -1
	s_and_b64 s[14:15], s[14:15], s[4:5]
	s_mov_b32 s13, 4
	s_lshl_b32 s4, s32, 6
	v_add_u32_e32 v54, s4, v144
	v_mul_lo_u32 v54, v54, s75
	v_mov_b32_e32 v55, v1
	v_lshl_add_u64 v[54:55], v[54:55], 1, v[88:89]
	global_load_dwordx4 v[182:185], v[54:55], off
	global_load_dwordx4 v[186:189], v[54:55], off offset:512
	s_cmp_eq_u64 s[14:15], 0
	s_cbranch_scc1 .Lsl3_xd_1
	s_ff1_i32_b64 s57, s[14:15]
	s_add_u32 s4, s14, -1
	s_addc_u32 s5, s15, -1
	s_and_b64 s[14:15], s[14:15], s[4:5]
	s_mov_b32 s13, 5
	s_lshl_b32 s4, s57, 6
	v_add_u32_e32 v54, s4, v144
	v_mul_lo_u32 v54, v54, s75
	v_mov_b32_e32 v55, v1
	v_lshl_add_u64 v[54:55], v[54:55], 1, v[88:89]
	global_load_dwordx4 v[194:197], v[54:55], off
	global_load_dwordx4 v[246:249], v[54:55], off offset:512
.Lsl3_xd_1:
.Lsl3_top:
	s_mov_b32 s26, s0
	s_mov_b32 s27, s1
	s_mov_b32 s28, s31
	s_mov_b32 s29, s32
	s_mov_b32 s56, s57
	s_mov_b32 s30, s13
	s_waitcnt lgkmcnt(0)
	s_barrier
	s_waitcnt vmcnt(0)
	ds_write_b128 v146, v[230:233] offset:16384
	ds_write_b128 v146, v[114:117] offset:26624
	s_cmp_lt_u32 s30, 2
	s_cbranch_scc1 .Lsl3_wd_2
	ds_write_b128 v146, v[134:137] offset:36864
	ds_write_b128 v146, v[156:159] offset:47104
	s_cmp_lt_u32 s30, 3
	s_cbranch_scc1 .Lsl3_wd_2
	ds_write_b128 v192, v[174:177] offset:8192
	ds_write_b128 v192, v[178:181] offset:18432
	s_cmp_lt_u32 s30, 4
	s_cbranch_scc1 .Lsl3_wd_2
	ds_write_b128 v192, v[182:185] offset:28672
	ds_write_b128 v192, v[186:189] offset:38912
	s_cmp_lt_u32 s30, 5
	s_cbranch_scc1 .Lsl3_wd_2
	ds_write_b128 v192, v[194:197] offset:49152
	ds_write_b128 v192, v[246:249] offset:59392
.Lsl3_wd_2:
	s_waitcnt lgkmcnt(0)
	s_barrier
	s_cmp_eq_u64 s[14:15], 0
	s_cbranch_scc1 .Lsl3_nonext_3
	s_mov_b32 s13, 0
	s_ff1_i32_b64 s0, s[14:15]
	s_add_u32 s4, s14, -1
	s_addc_u32 s5, s15, -1
	s_and_b64 s[14:15], s[14:15], s[4:5]
	s_mov_b32 s13, 1
	s_lshl_b32 s4, s0, 6
	v_add_u32_e32 v54, s4, v144
	v_mul_lo_u32 v54, v54, s75
	v_mov_b32_e32 v55, v1
	v_lshl_add_u64 v[54:55], v[54:55], 1, v[88:89]
	global_load_dwordx4 v[230:233], v[54:55], off
	global_load_dwordx4 v[114:117], v[54:55], off offset:512
	s_cmp_eq_u64 s[14:15], 0
	s_cbranch_scc1 .Lsl3_xd_5
	s_ff1_i32_b64 s1, s[14:15]
	s_add_u32 s4, s14, -1
	s_addc_u32 s5, s15, -1
	s_and_b64 s[14:15], s[14:15], s[4:5]
	s_mov_b32 s13, 2
	s_lshl_b32 s4, s1, 6
	v_add_u32_e32 v54, s4, v144
	v_mul_lo_u32 v54, v54, s75
	v_mov_b32_e32 v55, v1
	v_lshl_add_u64 v[54:55], v[54:55], 1, v[88:89]
	global_load_dwordx4 v[134:137], v[54:55], off
	global_load_dwordx4 v[156:159], v[54:55], off offset:512
	s_cmp_eq_u64 s[14:15], 0
	s_cbranch_scc1 .Lsl3_xd_5
	s_ff1_i32_b64 s31, s[14:15]
	s_add_u32 s4, s14, -1
	s_addc_u32 s5, s15, -1
	s_and_b64 s[14:15], s[14:15], s[4:5]
	s_mov_b32 s13, 3
	s_lshl_b32 s4, s31, 6
	v_add_u32_e32 v54, s4, v144
	v_mul_lo_u32 v54, v54, s75
	v_mov_b32_e32 v55, v1
	v_lshl_add_u64 v[54:55], v[54:55], 1, v[88:89]
	global_load_dwordx4 v[174:177], v[54:55], off
	global_load_dwordx4 v[178:181], v[54:55], off offset:512
	s_cmp_eq_u64 s[14:15], 0
	s_cbranch_scc1 .Lsl3_xd_5
	s_ff1_i32_b64 s32, s[14:15]
	s_add_u32 s4, s14, -1
	s_addc_u32 s5, s15, -1
	s_and_b64 s[14:15], s[14:15], s[4:5]
	s_mov_b32 s13, 4
	s_lshl_b32 s4, s32, 6
	v_add_u32_e32 v54, s4, v144
	v_mul_lo_u32 v54, v54, s75
	v_mov_b32_e32 v55, v1
	v_lshl_add_u64 v[54:55], v[54:55], 1, v[88:89]
	global_load_dwordx4 v[182:185], v[54:55], off
	global_load_dwordx4 v[186:189], v[54:55], off offset:512
	s_cmp_eq_u64 s[14:15], 0
	s_cbranch_scc1 .Lsl3_xd_5
	s_ff1_i32_b64 s57, s[14:15]
	s_add_u32 s4, s14, -1
	s_addc_u32 s5, s15, -1
	s_and_b64 s[14:15], s[14:15], s[4:5]
	s_mov_b32 s13, 5
	s_lshl_b32 s4, s57, 6
	v_add_u32_e32 v54, s4, v144
	v_mul_lo_u32 v54, v54, s75
	v_mov_b32_e32 v55, v1
	v_lshl_add_u64 v[54:55], v[54:55], 1, v[88:89]
	global_load_dwordx4 v[194:197], v[54:55], off
	global_load_dwordx4 v[246:249], v[54:55], off offset:512

; #define LAS __attribute__((address_space(3)))
; template <int D, class SF>
; __device__ __forceinline__ void attn_step(const bf16x8 (&qf)[D / 32], const LAS bf16_t* Ks, const LAS bf16_t* Vt, f32x4 (&o)[D / 16], float& m, float& lsum, float& alpha_out, bf16x8& pf0_out, bf16x8& pf1_out, const int lane, SF sf) {
;     ...
;     for (int ks = 0; ks < D / 32; ++ks) {
; #pragma unroll
;         for (int t = 0; t < 4; ++t) { const bf16x8 kf = *(const LAS bf16x8*)(Ks + (16 * t + c) * KSTR + ks * 32 + 8 * i); s[t] = mfma16(kf, qf[ks], s[t]); }
;     }
;     float v[16];
; #pragma unroll
;     for (int t = 0; t < 4; ++t)
; #pragma unroll
;         for (int r = 0; r < 4; ++r) v[4 * t + r] = sf(16 * t + 4 * i + r, s[t][r]);
;     float mx = fmaxf(fmaxf(fmaxf(v[0], v[1]), fmaxf(v[2], v[3])), fmaxf(fmaxf(v[4], v[5]), fmaxf(v[6], v[7])));
;     mx = fmaxf(mx, fmaxf(fmaxf(fmaxf(v[8], v[9]), fmaxf(v[10], v[11])), fmaxf(fmaxf(v[12], v[13]), fmaxf(v[14], v[15]))));
;     mx = rows_max(mx);
;     const float mnew = fmaxf(m, mx);
;     const float mc = fmaxf(mnew, -1e20f);
;     const float alpha = __builtin_amdgcn_exp2f(fmaxf(m, -1e20f) - mc);
;     float p[16], rs = 0.f;
; #pragma unroll
; __device__ __forceinline__ void nsa_unit(LAS unsigned char* lds, const Ctx& P, int l, int b, int hkv, int tb) {
;     ...
;             for (int sl = 0; sl < 2; ++sl) if (sl == 0 || hasb) {
;                 const int j = sl ? jb : ja; const LAS bf16_t* Ks = KV + sl * 9216; const LAS bf16_t* Vt = Ks + 4608;
;                 const bool far = t0 - (64 * j + 63) >= 790;
; #pragma unroll
;                 for (int sb = 0; sb < 2; ++sb) { const bool selj = (ms[sb] >> j) & 1ull; const int tqs = tq[sb];
;                     if (far) {
;                         if (__builtin_amdgcn_ballot_w64(selj) == 0ull) continue;
;                         attn_step<64>(qf[sb], Ks, Vt, o[sb], m[sb], lsum[sb], alpha, pf, pf1, lane,
;                             [&](int, float s) { return selj ? s * LOG2E + cfar : NEGBIG; });
;                     } else { const int kp0 = j * 64;
;                         attn_step<64>(qf[sb], Ks, Vt, o[sb], m[sb], lsum[sb], alpha, pf, pf1, lane,
;                             [&](int kk, float s) { const int dist = tqs - (kp0 + kk); return (selj && dist >= 0) ? s * LOG2E + lut[min((unsigned)dist, 1023u)] : NEGBIG; });
;                     }
;                 }
.Lsl3_slot_6:
	s_cmp_eq_u32 s40, 1
	s_cselect_b32 s20, s27, s26
	s_cmp_eq_u32 s40, 2
	s_cselect_b32 s20, s28, s20
	s_cmp_eq_u32 s40, 3
	s_cselect_b32 s20, s29, s20
	s_cmp_eq_u32 s40, 4
	s_cselect_b32 s20, s56, s20
	s_lshl_b32 s21, s20, 6
	s_mul_i32 s4, s40, 0x5000
	v_add_u32_e32 v190, s4, v102
	v_add_u32_e32 v191, s4, v104
	s_sub_i32 s4, s19, s21
	s_cmp_lt_i32 s4, 0
	s_cbranch_scc1 .Lsl3_diagx_9
	s_cmpk_lt_i32 s4, 0x316
	s_cbranch_scc1 .Lsl3_nearx_8
	v_lshrrev_b64 v[78:79], s20, v[18:19]
	v_and_b32_e32 v78, 1, v78
	v_cmp_eq_u32_e64 s[24:25], 1, v78
	s_cmp_eq_u64 s[24:25], 0
	s_cbranch_scc1 .Lsl3_skf_10
	ds_read_b128 v[198:201], v190 offset:16384
	ds_read_b128 v[206:209], v190 offset:18944
	ds_read_b128 v[202:205], v190 offset:16448
	ds_read_b128 v[210:213], v190 offset:19008
	ds_read_b128 v[214:217], v190 offset:21504
	ds_read_b128 v[222:225], v190 offset:24064
	ds_read_b128 v[218:221], v190 offset:21568
	ds_read_b128 v[226:229], v190 offset:24128
	s_waitcnt lgkmcnt(6)
	v_mfma_f32_16x16x32_bf16 v[54:57], v[198:201], v[2:5], 0
	v_mfma_f32_16x16x32_bf16 v[58:61], v[206:209], v[2:5], 0
	s_waitcnt lgkmcnt(4)
	v_mfma_f32_16x16x32_bf16 v[54:57], v[202:205], v[6:9], v[54:57]
	v_mfma_f32_16x16x32_bf16 v[58:61], v[210:213], v[6:9], v[58:61]
	s_waitcnt lgkmcnt(2)
	v_mfma_f32_16x16x32_bf16 v[62:65], v[214:217], v[2:5], 0
	v_mfma_f32_16x16x32_bf16 v[66:69], v[222:225], v[2:5], 0
	s_waitcnt lgkmcnt(0)
	v_mfma_f32_16x16x32_bf16 v[62:65], v[218:221], v[6:9], v[62:65]
	v_mfma_f32_16x16x32_bf16 v[66:69], v[226:229], v[6:9], v[66:69]
	ds_read_b64_tr_b16 v[198:199], v191 offset:26624
	ds_read_b64_tr_b16 v[200:201], v191 offset:29184
	ds_read_b64_tr_b16 v[202:203], v191 offset:31744
	ds_read_b64_tr_b16 v[204:205], v191 offset:34304
	ds_read_b64_tr_b16 v[206:207], v191 offset:26656
	ds_read_b64_tr_b16 v[208:209], v191 offset:29216
	ds_read_b64_tr_b16 v[210:211], v191 offset:31776
	ds_read_b64_tr_b16 v[212:213], v191 offset:34336
	ds_read_b64_tr_b16 v[214:215], v191 offset:26688
	ds_read_b64_tr_b16 v[216:217], v191 offset:29248
	ds_read_b64_tr_b16 v[218:219], v191 offset:31808
	ds_read_b64_tr_b16 v[220:221], v191 offset:34368
	ds_read_b64_tr_b16 v[222:223], v191 offset:26720
	ds_read_b64_tr_b16 v[224:225], v191 offset:29280
	ds_read_b64_tr_b16 v[226:227], v191 offset:31840
	ds_read_b64_tr_b16 v[228:229], v191 offset:34400
	v_max3_f32 v78, v54, v55, v56
	v_max3_f32 v79, v57, v58, v59
	v_max3_f32 v80, v60, v61, v62
	v_max3_f32 v81, v63, v64, v65
	v_max3_f32 v83, v66, v67, v68
	v_max3_f32 v78, v78, v79, v69
	v_max3_f32 v80, v80, v81, v83
	v_max_f32_e32 v78, v78, v80
	v_mov_b32_e32 v79, v78
	s_nop 1
	v_permlane16_swap_b32_e32 v78, v79
	v_max_f32_e32 v78, v78, v79
	v_mov_b32_e32 v79, v78
	s_nop 1
	v_permlane32_swap_b32_e32 v78, v79
	v_max_f32_e32 v78, v78, v79
	v_fmamk_f32 v78, v78, 0x3fb8aa3b, v92
	v_cndmask_b32_e64 v78, v243, v78, s[24:25]
	v_max_f32_e32 v80, v100, v78
	v_max_f32_e32 v82, 0xe0ad78ec, v100
	v_max_f32_e32 v81, 0xe0ad78ec, v80
	v_sub_f32_e32 v82, v82, v81
	v_mov_b32_e32 v100, v80
	v_exp_f32_e32 v82, v82
	v_sub_f32_e32 v83, v92, v81
	v_cndmask_b32_e64 v83, v243, v83, s[24:25]
	v_fmamk_f32 v54, v54, 0x3fb8aa3b, v83
	v_fmamk_f32 v55, v55, 0x3fb8aa3b, v83
	v_fmamk_f32 v56, v56, 0x3fb8aa3b, v83
	v_fmamk_f32 v57, v57, 0x3fb8aa3b, v83
	v_exp_f32_e32 v54, v54
	v_exp_f32_e32 v55, v55
	v_exp_f32_e32 v56, v56
	v_exp_f32_e32 v57, v57
	v_fmamk_f32 v58, v58, 0x3fb8aa3b, v83
	v_fmamk_f32 v59, v59, 0x3fb8aa3b, v83
	v_fmamk_f32 v60, v60, 0x3fb8aa3b, v83
	v_fmamk_f32 v61, v61, 0x3fb8aa3b, v83
	v_exp_f32_e32 v58, v58
	v_exp_f32_e32 v59, v59
	v_exp_f32_e32 v60, v60
	v_exp_f32_e32 v61, v61
	v_fmamk_f32 v62, v62, 0x3fb8aa3b, v83
	v_fmamk_f32 v63, v63, 0x3fb8aa3b, v83
	v_fmamk_f32 v64, v64, 0x3fb8aa3b, v83
	v_fmamk_f32 v65, v65, 0x3fb8aa3b, v83
	v_exp_f32_e32 v62, v62
	v_exp_f32_e32 v63, v63
	v_exp_f32_e32 v64, v64
	v_exp_f32_e32 v65, v65
	v_fmamk_f32 v66, v66, 0x3fb8aa3b, v83
	v_fmamk_f32 v67, v67, 0x3fb8aa3b, v83
	v_fmamk_f32 v68, v68, 0x3fb8aa3b, v83
	v_fmamk_f32 v69, v69, 0x3fb8aa3b, v83
	v_exp_f32_e32 v66, v66
	v_exp_f32_e32 v67, v67
	v_exp_f32_e32 v68, v68
	v_exp_f32_e32 v69, v69
	s_nop 0
	v_add_f32_e32 v78, v54, v55
	v_add_f32_e32 v79, v56, v57
	v_add_f32_e32 v80, v58, v59
	v_add_f32_e32 v81, v60, v61
	v_add_f32_e32 v78, v78, v62
	v_add_f32_e32 v79, v79, v63
	v_add_f32_e32 v80, v80, v64
	v_add_f32_e32 v81, v81, v65
	v_add_f32_e32 v78, v78, v66
	v_add_f32_e32 v79, v79, v67
	v_add_f32_e32 v80, v80, v68
	v_add_f32_e32 v81, v81, v69
	v_add_f32_e32 v78, v78, v79
	v_add_f32_e32 v80, v80, v81
	v_add_f32_e32 v78, v78, v80
	v_cvt_pk_bf16_f32 v70, v54, v55
	v_cvt_pk_bf16_f32 v71, v56, v57
	v_cvt_pk_bf16_f32 v72, v58, v59
	v_cvt_pk_bf16_f32 v73, v60, v61
	v_cvt_pk_bf16_f32 v74, v62, v63
	v_cvt_pk_bf16_f32 v75, v64, v65
	v_cvt_pk_bf16_f32 v76, v66, v67
	v_cvt_pk_bf16_f32 v77, v68, v69
	v_mov_b32_e32 v79, v78
	s_nop 1
	v_permlane16_swap_b32_e32 v78, v79
	v_add_f32_e32 v78, v78, v79
	v_mov_b32_e32 v79, v78
	s_nop 1
	v_permlane32_swap_b32_e32 v78, v79
	v_add_f32_e32 v78, v78, v79
	v_fma_f32 v106, v106, v82, v78
	v_cmp_neq_f32_e64 s[4:5], 1.0, v82
	s_cmp_eq_u64 s[4:5], 0
	s_cbranch_scc1 .Lsl3_nosc_11
	v_pk_mul_f32 v[38:39], v[38:39], v[82:83] op_sel_hi:[1,0]
	v_pk_mul_f32 v[40:41], v[40:41], v[82:83] op_sel_hi:[1,0]
	v_pk_mul_f32 v[42:43], v[42:43], v[82:83] op_sel_hi:[1,0]
	v_pk_mul_f32 v[44:45], v[44:45], v[82:83] op_sel_hi:[1,0]
	v_pk_mul_f32 v[46:47], v[46:47], v[82:83] op_sel_hi:[1,0]
	v_pk_mul_f32 v[48:49], v[48:49], v[82:83] op_sel_hi:[1,0]
	v_pk_mul_f32 v[50:51], v[50:51], v[82:83] op_sel_hi:[1,0]
	v_pk_mul_f32 v[52:53], v[52:53], v[82:83] op_sel_hi:[1,0]
